# v5a with the stage-prefetch loads retired by an exact vmcnt in front of the last epilogue store (7 / 15), so the relaxed peeled-iteration waits are provably safe
# speedup vs baseline: 1.0065x; 1.0061x over previous
; __device__ __forceinline__ unsigned cvt_pk_bf16(float lo, float hi) { unsigned r; asm volatile("v_cvt_pk_bf16_f32 %0, %1, %2" : "=v"(r) : "v"(lo), "v"(hi)); return r; }
;     __device__ __forceinline__ void operator()(const f32x4 (&acc)[2][2][4][2], const pg8::Unit& u, int wr, int wc, int fr, int fq) const {
;     ...
;                         u32x4 w; w.x = cvt_pk_bf16(v0[0], v0[1]); w.y = cvt_pk_bf16(v0[2], v0[3]); w.z = cvt_pk_bf16(v1[0], v1[1]); w.w = cvt_pk_bf16(v1[2], v1[3]);
;                         __builtin_nontemporal_store(w, (u32x4*)(rowp + (size_t)bj * bjs));
.LBB0_410:
	v_lshl_add_u64 v[148:149], s[86:87], 1, v[148:149]
	v_cvt_pk_bf16_f32 v150, v150, v151
	v_cvt_pk_bf16_f32 v151, v152, v153
	v_cvt_pk_bf16_f32 v152, v154, v155
	v_cvt_pk_bf16_f32 v153, v156, v157
	s_waitcnt vmcnt(15)
	global_store_dwordx4 v[148:149], v[150:153], off nt
	s_branch .LBB0_165

; __device__ __forceinline__ unsigned cvt_pk_bf16(float lo, float hi) { unsigned r; asm volatile("v_cvt_pk_bf16_f32 %0, %1, %2" : "=v"(r) : "v"(lo), "v"(hi)); return r; }
; __device__ __forceinline__ f32x4 gelu4(f32x4 v) { f32x2 a = gelu_pk((f32x2){v[0], v[1]}), b = gelu_pk((f32x2){v[2], v[3]}); return (f32x4){a.x, a.y, b.x, b.y}; }
; __device__ __forceinline__ f32x4 silu4(f32x4 v) { return v * sigm4(v); }
; __device__ __forceinline__ f32x2 gelu_pk(f32x2 v) {
;     const f32x2 av = __builtin_elementwise_abs(v), d = av * 0.2316418882f + 1.0f;
;     f32x2 t; t.x = __builtin_amdgcn_rcpf(d.x); t.y = __builtin_amdgcn_rcpf(d.y);
;     f32x2 q = t * 0.5307027145f + (-0.7265760135f); q = q * t + 0.7107068705f; q = q * t + (-0.142248368f); q = q * t + 0.127414796f; q = q * t;
;     const f32x2 s = (v * v) * (-0.72134752044f);
;     f32x2 e; e.x = __builtin_amdgcn_exp2f(s.x); e.y = __builtin_amdgcn_exp2f(s.y);
;     const f32x2 m = v * (q * e), r = v - m;
;     f32x2 o; o.x = v.x < 0.f ? m.x : r.x; o.y = v.y < 0.f ? m.y : r.y; return o;
;     __device__ __forceinline__ void operator()(const f32x4 (&acc)[2][2][4][2], const pg8::Unit& u, int wr, int wc, int fr, int fq) const {
;     ...
;                 for (int m = 0; m < 4; ++m) {
;                     bf16_t* rowp = base + (size_t)(row0 + ai * 128 + m * 16) * 1024;
;                     const f32x4 v0 = gelu4(acc[ai][0][m][0]) * silu4(acc[ai][1][m][0]), v1 = gelu4(acc[ai][0][m][1]) * silu4(acc[ai][1][m][1]);
;                     u32x4 w; w.x = cvt_pk_bf16(v0[0], v0[1]); w.y = cvt_pk_bf16(v0[2], v0[3]); w.z = cvt_pk_bf16(v1[0], v1[1]); w.w = cvt_pk_bf16(v1[2], v1[3]);
;                     __builtin_nontemporal_store(w, (u32x4*)rowp);
.Lepi_nb_b:
	v_pk_mul_f32 v[118:119], v[108:109], v[108:109]
	v_and_b32_e32 v120, 0x7fffffff, v110
	v_and_b32_e32 v115, 0x7fffffff, v109
	v_and_b32_e32 v114, 0x7fffffff, v108
	v_pk_fma_f32 v[114:115], v[114:115], s[28:29], 1.0 op_sel_hi:[1,0,0]
	v_pk_mul_f32 v[118:119], v[118:119], s[74:75] op_sel_hi:[1,0]
	v_rcp_f32_e32 v114, v114
	v_rcp_f32_e32 v115, v115
	v_exp_f32_e32 v118, v118
	v_exp_f32_e32 v119, v119
	v_pk_fma_f32 v[120:121], v[120:121], s[28:29], 1.0 op_sel_hi:[1,0,0]
	v_pk_fma_f32 v[116:117], v[114:115], s[30:31], v[150:151] op_sel_hi:[1,0,0]
	v_rcp_f32_e32 v120, v120
	v_pk_fma_f32 v[116:117], v[114:115], v[116:117], s[36:37] op_sel_hi:[1,1,0]
	v_rcp_f32_e32 v121, v121
	v_pk_fma_f32 v[116:117], v[114:115], v[116:117], s[50:51] op_sel_hi:[1,1,0]
	v_or_b32_e32 v112, 16, v146
	v_pk_fma_f32 v[116:117], v[114:115], v[116:117], s[72:73] op_sel_hi:[1,1,0]
	v_ashrrev_i32_e32 v113, 31, v112
	v_pk_mul_f32 v[114:115], v[114:115], v[116:117]
	v_pk_mul_f32 v[116:117], v[110:111], v[110:111]
	v_pk_mul_f32 v[114:115], v[118:119], v[114:115]
	v_pk_mul_f32 v[116:117], v[116:117], s[74:75] op_sel_hi:[1,0]
	v_pk_mul_f32 v[118:119], v[108:109], v[114:115]
	v_pk_fma_f32 v[114:115], v[108:109], v[114:115], v[108:109] neg_lo:[1,0,0] neg_hi:[1,0,0]
	v_exp_f32_e32 v116, v116
	v_cndmask_b32_e32 v108, v114, v118, vcc
	v_cmp_gt_f32_e32 vcc, 0, v109
	v_exp_f32_e32 v117, v117
	v_lshlrev_b64 v[112:113], 11, v[112:113]
	v_cndmask_b32_e32 v109, v115, v119, vcc
	v_pk_fma_f32 v[114:115], v[120:121], s[30:31], v[150:151] op_sel_hi:[1,0,0]
	v_cmp_gt_f32_e32 vcc, 0, v110
	v_pk_fma_f32 v[114:115], v[120:121], v[114:115], s[36:37] op_sel_hi:[1,1,0]
	v_lshl_add_u64 v[112:113], v[152:153], 0, v[112:113]
	v_pk_fma_f32 v[114:115], v[120:121], v[114:115], s[50:51] op_sel_hi:[1,1,0]
	s_mov_b32 s6, 0x40000
	v_pk_fma_f32 v[114:115], v[120:121], v[114:115], s[72:73] op_sel_hi:[1,1,0]
	s_nop 0
	v_pk_mul_f32 v[114:115], v[120:121], v[114:115]
	s_nop 0
	v_pk_mul_f32 v[114:115], v[116:117], v[114:115]
	s_nop 0
	v_pk_mul_f32 v[116:117], v[110:111], v[114:115]
	v_pk_fma_f32 v[114:115], v[110:111], v[114:115], v[110:111] neg_lo:[1,0,0] neg_hi:[1,0,0]
	s_nop 0
	v_cndmask_b32_e32 v110, v114, v116, vcc
	v_mul_f32_e32 v116, 0xbfb8aa3b, v105
	v_mul_f32_e32 v114, 0xbfb8aa3b, v104
	v_exp_f32_e32 v116, v116
	v_exp_f32_e32 v114, v114
	v_cmp_gt_f32_e32 vcc, 0, v111
	v_add_f32_e32 v114, 1.0, v114
	s_nop 0
	v_cndmask_b32_e32 v111, v115, v117, vcc
	v_add_f32_e32 v115, 1.0, v116
	v_mul_f32_e32 v116, 0xbfb8aa3b, v106
	v_mul_f32_e32 v117, 0xbfb8aa3b, v107
	v_exp_f32_e32 v116, v116
	v_exp_f32_e32 v117, v117
	v_rcp_f32_e32 v114, v114
	v_rcp_f32_e32 v115, v115
	v_add_f32_e32 v116, 1.0, v116
	v_add_f32_e32 v117, 1.0, v117
	v_rcp_f32_e32 v116, v116
	v_rcp_f32_e32 v117, v117
	v_pk_mul_f32 v[104:105], v[104:105], v[114:115]
	v_and_b32_e32 v115, 0x7fffffff, v101
	v_and_b32_e32 v114, 0x7fffffff, v100
	v_pk_fma_f32 v[114:115], v[114:115], s[28:29], 1.0 op_sel_hi:[1,0,0]
	v_pk_mul_f32 v[106:107], v[106:107], v[116:117]
	v_rcp_f32_e32 v114, v114
	v_rcp_f32_e32 v115, v115
	v_pk_mul_f32 v[106:107], v[110:111], v[106:107]
	v_pk_mul_f32 v[110:111], v[100:101], v[100:101]
	v_pk_mul_f32 v[104:105], v[108:109], v[104:105]
	v_pk_fma_f32 v[108:109], v[114:115], s[30:31], v[150:151] op_sel_hi:[1,0,0]
	v_pk_mul_f32 v[110:111], v[110:111], s[74:75] op_sel_hi:[1,0]
	v_pk_fma_f32 v[108:109], v[114:115], v[108:109], s[36:37] op_sel_hi:[1,1,0]
	v_exp_f32_e32 v110, v110
	v_exp_f32_e32 v111, v111
	v_pk_fma_f32 v[108:109], v[114:115], v[108:109], s[50:51] op_sel_hi:[1,1,0]
	v_and_b32_e32 v117, 0x7fffffff, v103
	v_and_b32_e32 v116, 0x7fffffff, v102
	v_pk_fma_f32 v[108:109], v[114:115], v[108:109], s[72:73] op_sel_hi:[1,1,0]
	v_pk_fma_f32 v[116:117], v[116:117], s[28:29], 1.0 op_sel_hi:[1,0,0]
	v_pk_mul_f32 v[108:109], v[114:115], v[108:109]
	v_rcp_f32_e32 v116, v116
	v_rcp_f32_e32 v117, v117
	v_pk_mul_f32 v[108:109], v[110:111], v[108:109]
	v_cmp_gt_f32_e32 vcc, 0, v100
	v_pk_mul_f32 v[110:111], v[100:101], v[108:109]
	v_pk_fma_f32 v[108:109], v[100:101], v[108:109], v[100:101] neg_lo:[1,0,0] neg_hi:[1,0,0]
	v_pk_mul_f32 v[114:115], v[102:103], v[102:103]
	v_cndmask_b32_e32 v100, v108, v110, vcc
	v_cmp_gt_f32_e32 vcc, 0, v101
	s_nop 1
	v_cndmask_b32_e32 v101, v109, v111, vcc
	v_pk_fma_f32 v[108:109], v[116:117], s[30:31], v[150:151] op_sel_hi:[1,0,0]
	v_pk_mul_f32 v[110:111], v[114:115], s[74:75] op_sel_hi:[1,0]
	v_pk_fma_f32 v[108:109], v[116:117], v[108:109], s[36:37] op_sel_hi:[1,1,0]
	v_exp_f32_e32 v110, v110
	v_exp_f32_e32 v111, v111
	v_pk_fma_f32 v[108:109], v[116:117], v[108:109], s[50:51] op_sel_hi:[1,1,0]
	v_mul_f32_e32 v114, 0xbfb8aa3b, v96
	v_pk_fma_f32 v[108:109], v[116:117], v[108:109], s[72:73] op_sel_hi:[1,1,0]
	v_exp_f32_e32 v114, v114
	v_mul_f32_e32 v115, 0xbfb8aa3b, v97
	v_pk_mul_f32 v[108:109], v[116:117], v[108:109]
	v_exp_f32_e32 v115, v115
	v_pk_mul_f32 v[108:109], v[110:111], v[108:109]
	v_cmp_gt_f32_e32 vcc, 0, v102
	v_pk_mul_f32 v[110:111], v[102:103], v[108:109]
	v_pk_fma_f32 v[108:109], v[102:103], v[108:109], v[102:103] neg_lo:[1,0,0] neg_hi:[1,0,0]
	s_nop 0
	v_cndmask_b32_e32 v102, v108, v110, vcc
	v_add_f32_e32 v108, 1.0, v114
	v_mul_f32_e32 v110, 0xbfb8aa3b, v98
	v_rcp_f32_e32 v114, v108
	v_add_f32_e32 v108, 1.0, v115
	v_exp_f32_e32 v110, v110
	v_mul_f32_e32 v115, 0xbfb8aa3b, v99
	v_exp_f32_e32 v117, v115
	v_rcp_f32_e32 v115, v108
	v_add_f32_e32 v108, 1.0, v110
	v_rcp_f32_e32 v116, v108
	v_add_f32_e32 v108, 1.0, v117
	v_rcp_f32_e32 v117, v108
	v_cmp_gt_f32_e32 vcc, 0, v103
	v_pk_mul_f32 v[96:97], v[96:97], v[114:115]
	v_pk_mul_f32 v[98:99], v[98:99], v[116:117]
	v_cndmask_b32_e32 v103, v109, v111, vcc
; __device__ __forceinline__ unsigned cvt_pk_bf16(float lo, float hi) { unsigned r; asm volatile("v_cvt_pk_bf16_f32 %0, %1, %2" : "=v"(r) : "v"(lo), "v"(hi)); return r; }
; __device__ __forceinline__ f32x4 gelu4(f32x4 v) { f32x2 a = gelu_pk((f32x2){v[0], v[1]}), b = gelu_pk((f32x2){v[2], v[3]}); return (f32x4){a.x, a.y, b.x, b.y}; }
; __device__ __forceinline__ f32x4 silu4(f32x4 v) { return v * sigm4(v); }
;     __device__ __forceinline__ void operator()(const f32x4 (&acc)[2][2][4][2], const pg8::Unit& u, int wr, int wc, int fr, int fq) const {
;     ...
;                 for (int m = 0; m < 4; ++m) {
;                     bf16_t* rowp = base + (size_t)(row0 + ai * 128 + m * 16) * 1024;
;                     const f32x4 v0 = gelu4(acc[ai][0][m][0]) * silu4(acc[ai][1][m][0]), v1 = gelu4(acc[ai][0][m][1]) * silu4(acc[ai][1][m][1]);
;                     u32x4 w; w.x = cvt_pk_bf16(v0[0], v0[1]); w.y = cvt_pk_bf16(v0[2], v0[3]); w.z = cvt_pk_bf16(v1[0], v1[1]); w.w = cvt_pk_bf16(v1[2], v1[3]);
;                     __builtin_nontemporal_store(w, (u32x4*)rowp);
	v_pk_mul_f32 v[102:103], v[102:103], v[98:99]
	v_pk_mul_f32 v[98:99], v[100:101], v[96:97]
	v_cvt_pk_bf16_f32 v96, v104, v105
	v_cvt_pk_bf16_f32 v97, v106, v107
	v_and_b32_e32 v105, 0x7fffffff, v95
	v_cvt_pk_bf16_f32 v98, v98, v99
	v_cvt_pk_bf16_f32 v99, v102, v103
	global_store_dwordx4 v[112:113], v[96:99], off nt
	v_pk_mul_f32 v[102:103], v[92:93], v[92:93]
	v_and_b32_e32 v104, 0x7fffffff, v94
	v_and_b32_e32 v99, 0x7fffffff, v93
	v_and_b32_e32 v98, 0x7fffffff, v92
	v_pk_fma_f32 v[98:99], v[98:99], s[28:29], 1.0 op_sel_hi:[1,0,0]
	v_pk_mul_f32 v[102:103], v[102:103], s[74:75] op_sel_hi:[1,0]
	v_rcp_f32_e32 v98, v98
	v_rcp_f32_e32 v99, v99
	v_exp_f32_e32 v102, v102
	v_exp_f32_e32 v103, v103
	v_pk_fma_f32 v[104:105], v[104:105], s[28:29], 1.0 op_sel_hi:[1,0,0]
	v_pk_fma_f32 v[100:101], v[98:99], s[30:31], v[150:151] op_sel_hi:[1,0,0]
	v_rcp_f32_e32 v104, v104
	v_pk_fma_f32 v[100:101], v[98:99], v[100:101], s[36:37] op_sel_hi:[1,1,0]
	v_rcp_f32_e32 v105, v105
	v_pk_fma_f32 v[100:101], v[98:99], v[100:101], s[50:51] op_sel_hi:[1,1,0]
	v_cmp_gt_f32_e32 vcc, 0, v92
	v_pk_fma_f32 v[100:101], v[98:99], v[100:101], s[72:73] op_sel_hi:[1,1,0]
	v_or_b32_e32 v96, 32, v146
	v_pk_mul_f32 v[98:99], v[98:99], v[100:101]
	v_pk_mul_f32 v[100:101], v[94:95], v[94:95]
	v_pk_mul_f32 v[98:99], v[102:103], v[98:99]
	v_pk_mul_f32 v[100:101], v[100:101], s[74:75] op_sel_hi:[1,0]
	v_pk_mul_f32 v[102:103], v[92:93], v[98:99]
	v_pk_fma_f32 v[98:99], v[92:93], v[98:99], v[92:93] neg_lo:[1,0,0] neg_hi:[1,0,0]
	v_exp_f32_e32 v100, v100
	v_cndmask_b32_e32 v92, v98, v102, vcc
	v_cmp_gt_f32_e32 vcc, 0, v93
	v_exp_f32_e32 v101, v101
	v_ashrrev_i32_e32 v97, 31, v96
	v_cndmask_b32_e32 v93, v99, v103, vcc
	v_pk_fma_f32 v[98:99], v[104:105], s[30:31], v[150:151] op_sel_hi:[1,0,0]
	v_cmp_gt_f32_e32 vcc, 0, v94
	v_pk_fma_f32 v[98:99], v[104:105], v[98:99], s[36:37] op_sel_hi:[1,1,0]
	v_lshlrev_b64 v[96:97], 11, v[96:97]
	v_pk_fma_f32 v[98:99], v[104:105], v[98:99], s[50:51] op_sel_hi:[1,1,0]
	v_lshl_add_u64 v[96:97], v[152:153], 0, v[96:97]
	v_pk_fma_f32 v[98:99], v[104:105], v[98:99], s[72:73] op_sel_hi:[1,1,0]
	s_nop 0
	v_pk_mul_f32 v[98:99], v[104:105], v[98:99]
	s_nop 0
	v_pk_mul_f32 v[98:99], v[100:101], v[98:99]
	s_nop 0
	v_pk_mul_f32 v[100:101], v[94:95], v[98:99]
	v_pk_fma_f32 v[98:99], v[94:95], v[98:99], v[94:95] neg_lo:[1,0,0] neg_hi:[1,0,0]
	s_nop 0
	v_cndmask_b32_e32 v94, v98, v100, vcc
	v_mul_f32_e32 v100, 0xbfb8aa3b, v89
	v_mul_f32_e32 v98, 0xbfb8aa3b, v88
	v_exp_f32_e32 v100, v100
	v_exp_f32_e32 v98, v98
	v_cmp_gt_f32_e32 vcc, 0, v95
	v_add_f32_e32 v98, 1.0, v98
	s_nop 0
	v_cndmask_b32_e32 v95, v99, v101, vcc
	v_add_f32_e32 v99, 1.0, v100
	v_mul_f32_e32 v100, 0xbfb8aa3b, v90
	v_mul_f32_e32 v101, 0xbfb8aa3b, v91
	v_exp_f32_e32 v100, v100
	v_exp_f32_e32 v101, v101
	v_rcp_f32_e32 v98, v98
	v_rcp_f32_e32 v99, v99
	v_add_f32_e32 v100, 1.0, v100
	v_add_f32_e32 v101, 1.0, v101
	v_rcp_f32_e32 v100, v100
	v_rcp_f32_e32 v101, v101
	v_pk_mul_f32 v[88:89], v[88:89], v[98:99]
	v_and_b32_e32 v99, 0x7fffffff, v85
	v_and_b32_e32 v98, 0x7fffffff, v84
	v_pk_fma_f32 v[98:99], v[98:99], s[28:29], 1.0 op_sel_hi:[1,0,0]
	v_pk_mul_f32 v[90:91], v[90:91], v[100:101]
	v_rcp_f32_e32 v98, v98
	v_rcp_f32_e32 v99, v99
	v_pk_mul_f32 v[90:91], v[94:95], v[90:91]
	v_pk_mul_f32 v[94:95], v[84:85], v[84:85]
	v_pk_mul_f32 v[88:89], v[92:93], v[88:89]
	v_pk_fma_f32 v[92:93], v[98:99], s[30:31], v[150:151] op_sel_hi:[1,0,0]
	v_pk_mul_f32 v[94:95], v[94:95], s[74:75] op_sel_hi:[1,0]
	v_pk_fma_f32 v[92:93], v[98:99], v[92:93], s[36:37] op_sel_hi:[1,1,0]
	v_exp_f32_e32 v94, v94
	v_exp_f32_e32 v95, v95
	v_pk_fma_f32 v[92:93], v[98:99], v[92:93], s[50:51] op_sel_hi:[1,1,0]
	v_and_b32_e32 v101, 0x7fffffff, v87
	v_and_b32_e32 v100, 0x7fffffff, v86
	v_pk_fma_f32 v[92:93], v[98:99], v[92:93], s[72:73] op_sel_hi:[1,1,0]
	v_pk_fma_f32 v[100:101], v[100:101], s[28:29], 1.0 op_sel_hi:[1,0,0]
	v_pk_mul_f32 v[92:93], v[98:99], v[92:93]
	v_rcp_f32_e32 v100, v100
	v_rcp_f32_e32 v101, v101
	v_pk_mul_f32 v[92:93], v[94:95], v[92:93]
	v_cmp_gt_f32_e32 vcc, 0, v84
	v_pk_mul_f32 v[94:95], v[84:85], v[92:93]
	v_pk_fma_f32 v[92:93], v[84:85], v[92:93], v[84:85] neg_lo:[1,0,0] neg_hi:[1,0,0]
	v_pk_mul_f32 v[98:99], v[86:87], v[86:87]
	v_cndmask_b32_e32 v84, v92, v94, vcc
	v_cmp_gt_f32_e32 vcc, 0, v85
	s_nop 1
	v_cndmask_b32_e32 v85, v93, v95, vcc
	v_pk_fma_f32 v[92:93], v[100:101], s[30:31], v[150:151] op_sel_hi:[1,0,0]
	v_pk_mul_f32 v[94:95], v[98:99], s[74:75] op_sel_hi:[1,0]
	v_pk_fma_f32 v[92:93], v[100:101], v[92:93], s[36:37] op_sel_hi:[1,1,0]
	v_exp_f32_e32 v94, v94
	v_exp_f32_e32 v95, v95
	v_pk_fma_f32 v[92:93], v[100:101], v[92:93], s[50:51] op_sel_hi:[1,1,0]
	v_mul_f32_e32 v98, 0xbfb8aa3b, v80
	v_pk_fma_f32 v[92:93], v[100:101], v[92:93], s[72:73] op_sel_hi:[1,1,0]
	v_exp_f32_e32 v98, v98
	v_mul_f32_e32 v99, 0xbfb8aa3b, v81
	v_pk_mul_f32 v[92:93], v[100:101], v[92:93]
	v_exp_f32_e32 v99, v99
	v_pk_mul_f32 v[92:93], v[94:95], v[92:93]
	v_cmp_gt_f32_e32 vcc, 0, v86
	v_pk_mul_f32 v[94:95], v[86:87], v[92:93]
	v_pk_fma_f32 v[92:93], v[86:87], v[92:93], v[86:87] neg_lo:[1,0,0] neg_hi:[1,0,0]
	s_nop 0
	v_cndmask_b32_e32 v86, v92, v94, vcc
	v_add_f32_e32 v92, 1.0, v98
	v_mul_f32_e32 v94, 0xbfb8aa3b, v82
	v_rcp_f32_e32 v98, v92
	v_add_f32_e32 v92, 1.0, v99
	v_exp_f32_e32 v94, v94
	v_mul_f32_e32 v99, 0xbfb8aa3b, v83
	v_exp_f32_e32 v101, v99
	v_rcp_f32_e32 v99, v92
	v_add_f32_e32 v92, 1.0, v94
	v_rcp_f32_e32 v100, v92
	v_add_f32_e32 v92, 1.0, v101
	v_rcp_f32_e32 v101, v92
	v_cmp_gt_f32_e32 vcc, 0, v87
	v_pk_mul_f32 v[80:81], v[80:81], v[98:99]
	v_pk_mul_f32 v[82:83], v[82:83], v[100:101]
	v_cndmask_b32_e32 v87, v93, v95, vcc
; __device__ __forceinline__ unsigned cvt_pk_bf16(float lo, float hi) { unsigned r; asm volatile("v_cvt_pk_bf16_f32 %0, %1, %2" : "=v"(r) : "v"(lo), "v"(hi)); return r; }
; __device__ __forceinline__ f32x4 gelu4(f32x4 v) { f32x2 a = gelu_pk((f32x2){v[0], v[1]}), b = gelu_pk((f32x2){v[2], v[3]}); return (f32x4){a.x, a.y, b.x, b.y}; }
; __device__ __forceinline__ f32x4 silu4(f32x4 v) { return v * sigm4(v); }
;     __device__ __forceinline__ void operator()(const f32x4 (&acc)[2][2][4][2], const pg8::Unit& u, int wr, int wc, int fr, int fq) const {
;     ...
;                 for (int m = 0; m < 4; ++m) {
;                     bf16_t* rowp = base + (size_t)(row0 + ai * 128 + m * 16) * 1024;
;                     const f32x4 v0 = gelu4(acc[ai][0][m][0]) * silu4(acc[ai][1][m][0]), v1 = gelu4(acc[ai][0][m][1]) * silu4(acc[ai][1][m][1]);
;                     u32x4 w; w.x = cvt_pk_bf16(v0[0], v0[1]); w.y = cvt_pk_bf16(v0[2], v0[3]); w.z = cvt_pk_bf16(v1[0], v1[1]); w.w = cvt_pk_bf16(v1[2], v1[3]);
;                     __builtin_nontemporal_store(w, (u32x4*)rowp);
	v_pk_mul_f32 v[86:87], v[86:87], v[82:83]
	v_pk_mul_f32 v[82:83], v[84:85], v[80:81]
	v_cvt_pk_bf16_f32 v80, v88, v89
	v_cvt_pk_bf16_f32 v81, v90, v91
	v_and_b32_e32 v89, 0x7fffffff, v79
	v_cvt_pk_bf16_f32 v82, v82, v83
	v_cvt_pk_bf16_f32 v83, v86, v87
	global_store_dwordx4 v[96:97], v[80:83], off nt
	v_pk_mul_f32 v[86:87], v[76:77], v[76:77]
	v_and_b32_e32 v88, 0x7fffffff, v78
	v_and_b32_e32 v83, 0x7fffffff, v77
	v_and_b32_e32 v82, 0x7fffffff, v76
	v_pk_fma_f32 v[82:83], v[82:83], s[28:29], 1.0 op_sel_hi:[1,0,0]
	v_pk_mul_f32 v[86:87], v[86:87], s[74:75] op_sel_hi:[1,0]
	v_rcp_f32_e32 v82, v82
	v_rcp_f32_e32 v83, v83
	v_exp_f32_e32 v86, v86
	v_exp_f32_e32 v87, v87
	v_pk_fma_f32 v[88:89], v[88:89], s[28:29], 1.0 op_sel_hi:[1,0,0]
	v_pk_fma_f32 v[84:85], v[82:83], s[30:31], v[150:151] op_sel_hi:[1,0,0]
	v_rcp_f32_e32 v88, v88
	v_pk_fma_f32 v[84:85], v[82:83], v[84:85], s[36:37] op_sel_hi:[1,1,0]
	v_rcp_f32_e32 v89, v89
	v_pk_fma_f32 v[84:85], v[82:83], v[84:85], s[50:51] op_sel_hi:[1,1,0]
	v_cmp_gt_f32_e32 vcc, 0, v76
	v_pk_fma_f32 v[84:85], v[82:83], v[84:85], s[72:73] op_sel_hi:[1,1,0]
	v_or_b32_e32 v80, 48, v146
	v_pk_mul_f32 v[82:83], v[82:83], v[84:85]
	v_pk_mul_f32 v[84:85], v[78:79], v[78:79]
	v_pk_mul_f32 v[82:83], v[86:87], v[82:83]
	v_pk_mul_f32 v[84:85], v[84:85], s[74:75] op_sel_hi:[1,0]
	v_pk_mul_f32 v[86:87], v[76:77], v[82:83]
	v_pk_fma_f32 v[82:83], v[76:77], v[82:83], v[76:77] neg_lo:[1,0,0] neg_hi:[1,0,0]
	v_exp_f32_e32 v84, v84
	v_cndmask_b32_e32 v76, v82, v86, vcc
	v_cmp_gt_f32_e32 vcc, 0, v77
	v_exp_f32_e32 v85, v85
	v_ashrrev_i32_e32 v81, 31, v80
	v_cndmask_b32_e32 v77, v83, v87, vcc
	v_pk_fma_f32 v[82:83], v[88:89], s[30:31], v[150:151] op_sel_hi:[1,0,0]
	v_cmp_gt_f32_e32 vcc, 0, v78
	v_pk_fma_f32 v[82:83], v[88:89], v[82:83], s[36:37] op_sel_hi:[1,1,0]
	v_lshlrev_b64 v[80:81], 11, v[80:81]
	v_pk_fma_f32 v[82:83], v[88:89], v[82:83], s[50:51] op_sel_hi:[1,1,0]
	v_lshl_add_u64 v[80:81], v[152:153], 0, v[80:81]
	v_pk_fma_f32 v[82:83], v[88:89], v[82:83], s[72:73] op_sel_hi:[1,1,0]
	s_nop 0
	v_pk_mul_f32 v[82:83], v[88:89], v[82:83]
	s_nop 0
	v_pk_mul_f32 v[82:83], v[84:85], v[82:83]
	s_nop 0
	v_pk_mul_f32 v[84:85], v[78:79], v[82:83]
	v_pk_fma_f32 v[82:83], v[78:79], v[82:83], v[78:79] neg_lo:[1,0,0] neg_hi:[1,0,0]
	s_nop 0
	v_cndmask_b32_e32 v78, v82, v84, vcc
	v_mul_f32_e32 v84, 0xbfb8aa3b, v73
	v_mul_f32_e32 v82, 0xbfb8aa3b, v72
	v_exp_f32_e32 v84, v84
	v_exp_f32_e32 v82, v82
	v_cmp_gt_f32_e32 vcc, 0, v79
	v_add_f32_e32 v82, 1.0, v82
	s_nop 0
	v_cndmask_b32_e32 v79, v83, v85, vcc
	v_add_f32_e32 v83, 1.0, v84
	v_mul_f32_e32 v84, 0xbfb8aa3b, v74
	v_mul_f32_e32 v85, 0xbfb8aa3b, v75
	v_exp_f32_e32 v84, v84
	v_exp_f32_e32 v85, v85
	v_rcp_f32_e32 v82, v82
	v_rcp_f32_e32 v83, v83
	v_add_f32_e32 v84, 1.0, v84
	v_add_f32_e32 v85, 1.0, v85
	v_rcp_f32_e32 v84, v84
	v_rcp_f32_e32 v85, v85
	v_pk_mul_f32 v[72:73], v[72:73], v[82:83]
	v_and_b32_e32 v83, 0x7fffffff, v69
	v_and_b32_e32 v82, 0x7fffffff, v68
	v_pk_fma_f32 v[82:83], v[82:83], s[28:29], 1.0 op_sel_hi:[1,0,0]
	v_pk_mul_f32 v[74:75], v[74:75], v[84:85]
	v_rcp_f32_e32 v82, v82
	v_rcp_f32_e32 v83, v83
	v_pk_mul_f32 v[74:75], v[78:79], v[74:75]
	v_pk_mul_f32 v[78:79], v[68:69], v[68:69]
	v_pk_mul_f32 v[72:73], v[76:77], v[72:73]
	v_pk_fma_f32 v[76:77], v[82:83], s[30:31], v[150:151] op_sel_hi:[1,0,0]
	v_pk_mul_f32 v[78:79], v[78:79], s[74:75] op_sel_hi:[1,0]
	v_pk_fma_f32 v[76:77], v[82:83], v[76:77], s[36:37] op_sel_hi:[1,1,0]
	v_exp_f32_e32 v78, v78
	v_exp_f32_e32 v79, v79
	v_pk_fma_f32 v[76:77], v[82:83], v[76:77], s[50:51] op_sel_hi:[1,1,0]
	v_and_b32_e32 v85, 0x7fffffff, v71
	v_and_b32_e32 v84, 0x7fffffff, v70
	v_pk_fma_f32 v[76:77], v[82:83], v[76:77], s[72:73] op_sel_hi:[1,1,0]
	v_pk_fma_f32 v[84:85], v[84:85], s[28:29], 1.0 op_sel_hi:[1,0,0]
	v_pk_mul_f32 v[76:77], v[82:83], v[76:77]
	v_rcp_f32_e32 v84, v84
	v_rcp_f32_e32 v85, v85
	v_pk_mul_f32 v[76:77], v[78:79], v[76:77]
	v_cmp_gt_f32_e32 vcc, 0, v68
	v_pk_mul_f32 v[78:79], v[68:69], v[76:77]
	v_pk_fma_f32 v[76:77], v[68:69], v[76:77], v[68:69] neg_lo:[1,0,0] neg_hi:[1,0,0]
	v_pk_mul_f32 v[82:83], v[70:71], v[70:71]
	v_cndmask_b32_e32 v68, v76, v78, vcc
	v_cmp_gt_f32_e32 vcc, 0, v69
	s_nop 1
	v_cndmask_b32_e32 v69, v77, v79, vcc
	v_pk_fma_f32 v[76:77], v[84:85], s[30:31], v[150:151] op_sel_hi:[1,0,0]
	v_pk_mul_f32 v[78:79], v[82:83], s[74:75] op_sel_hi:[1,0]
	v_pk_fma_f32 v[76:77], v[84:85], v[76:77], s[36:37] op_sel_hi:[1,1,0]
	v_exp_f32_e32 v78, v78
	v_exp_f32_e32 v79, v79
	v_pk_fma_f32 v[76:77], v[84:85], v[76:77], s[50:51] op_sel_hi:[1,1,0]
	v_mul_f32_e32 v82, 0xbfb8aa3b, v64
	v_pk_fma_f32 v[76:77], v[84:85], v[76:77], s[72:73] op_sel_hi:[1,1,0]
	v_exp_f32_e32 v82, v82
	v_mul_f32_e32 v83, 0xbfb8aa3b, v65
	v_pk_mul_f32 v[76:77], v[84:85], v[76:77]
	v_exp_f32_e32 v83, v83
	v_pk_mul_f32 v[76:77], v[78:79], v[76:77]
	v_cmp_gt_f32_e32 vcc, 0, v70
	v_pk_mul_f32 v[78:79], v[70:71], v[76:77]
	v_pk_fma_f32 v[76:77], v[70:71], v[76:77], v[70:71] neg_lo:[1,0,0] neg_hi:[1,0,0]
	s_nop 0
	v_cndmask_b32_e32 v70, v76, v78, vcc
	v_add_f32_e32 v76, 1.0, v82
	v_mul_f32_e32 v78, 0xbfb8aa3b, v66
	v_rcp_f32_e32 v82, v76
	v_add_f32_e32 v76, 1.0, v83
	v_exp_f32_e32 v78, v78
	v_mul_f32_e32 v83, 0xbfb8aa3b, v67
	v_exp_f32_e32 v85, v83
	v_rcp_f32_e32 v83, v76
	v_add_f32_e32 v76, 1.0, v78
	v_rcp_f32_e32 v84, v76
	v_add_f32_e32 v76, 1.0, v85
	v_rcp_f32_e32 v85, v76
	v_cmp_gt_f32_e32 vcc, 0, v71
	v_pk_mul_f32 v[64:65], v[64:65], v[82:83]
	v_pk_mul_f32 v[66:67], v[66:67], v[84:85]
	v_cndmask_b32_e32 v71, v77, v79, vcc
	v_pk_mul_f32 v[70:71], v[70:71], v[66:67]
	v_pk_mul_f32 v[66:67], v[68:69], v[64:65]
	v_and_b32_e32 v69, 0x7fffffff, v61
; __device__ __forceinline__ unsigned cvt_pk_bf16(float lo, float hi) { unsigned r; asm volatile("v_cvt_pk_bf16_f32 %0, %1, %2" : "=v"(r) : "v"(lo), "v"(hi)); return r; }
; __device__ __forceinline__ f32x4 gelu4(f32x4 v) { f32x2 a = gelu_pk((f32x2){v[0], v[1]}), b = gelu_pk((f32x2){v[2], v[3]}); return (f32x4){a.x, a.y, b.x, b.y}; }
; __device__ __forceinline__ f32x4 silu4(f32x4 v) { return v * sigm4(v); }
;     __device__ __forceinline__ void operator()(const f32x4 (&acc)[2][2][4][2], const pg8::Unit& u, int wr, int wc, int fr, int fq) const {
;     ...
;                 for (int m = 0; m < 4; ++m) {
;                     bf16_t* rowp = base + (size_t)(row0 + ai * 128 + m * 16) * 1024;
;                     const f32x4 v0 = gelu4(acc[ai][0][m][0]) * silu4(acc[ai][1][m][0]), v1 = gelu4(acc[ai][0][m][1]) * silu4(acc[ai][1][m][1]);
;                     u32x4 w; w.x = cvt_pk_bf16(v0[0], v0[1]); w.y = cvt_pk_bf16(v0[2], v0[3]); w.z = cvt_pk_bf16(v1[0], v1[1]); w.w = cvt_pk_bf16(v1[2], v1[3]);
;                     __builtin_nontemporal_store(w, (u32x4*)rowp);
	v_and_b32_e32 v68, 0x7fffffff, v60
	v_pk_fma_f32 v[68:69], v[68:69], s[28:29], 1.0 op_sel_hi:[1,0,0]
	v_cvt_pk_bf16_f32 v64, v72, v73
	v_cvt_pk_bf16_f32 v65, v74, v75
	v_cvt_pk_bf16_f32 v66, v66, v67
	v_cvt_pk_bf16_f32 v67, v70, v71
	global_store_dwordx4 v[80:81], v[64:67], off nt
	v_rcp_f32_e32 v68, v68
	v_rcp_f32_e32 v69, v69
	v_pk_mul_f32 v[66:67], v[60:61], v[60:61]
	v_and_b32_e32 v71, 0x7fffffff, v63
	v_pk_mul_f32 v[66:67], v[66:67], s[74:75] op_sel_hi:[1,0]
	v_pk_fma_f32 v[64:65], v[68:69], s[30:31], v[150:151] op_sel_hi:[1,0,0]
	v_exp_f32_e32 v66, v66
	v_pk_fma_f32 v[64:65], v[68:69], v[64:65], s[36:37] op_sel_hi:[1,1,0]
	v_exp_f32_e32 v67, v67
	v_pk_fma_f32 v[64:65], v[68:69], v[64:65], s[50:51] op_sel_hi:[1,1,0]
	v_and_b32_e32 v70, 0x7fffffff, v62
	v_pk_fma_f32 v[64:65], v[68:69], v[64:65], s[72:73] op_sel_hi:[1,1,0]
	v_pk_fma_f32 v[70:71], v[70:71], s[28:29], 1.0 op_sel_hi:[1,0,0]
	v_pk_mul_f32 v[64:65], v[68:69], v[64:65]
	v_rcp_f32_e32 v70, v70
	v_rcp_f32_e32 v71, v71
	v_pk_mul_f32 v[64:65], v[66:67], v[64:65]
	v_cmp_gt_f32_e32 vcc, 0, v60
	v_pk_mul_f32 v[66:67], v[60:61], v[64:65]
	v_pk_fma_f32 v[64:65], v[60:61], v[64:65], v[60:61] neg_lo:[1,0,0] neg_hi:[1,0,0]
	v_pk_mul_f32 v[68:69], v[62:63], v[62:63]
	v_cndmask_b32_e32 v60, v64, v66, vcc
	v_cmp_gt_f32_e32 vcc, 0, v61
	s_nop 1
	v_cndmask_b32_e32 v61, v65, v67, vcc
	v_pk_fma_f32 v[64:65], v[70:71], s[30:31], v[150:151] op_sel_hi:[1,0,0]
	v_pk_mul_f32 v[66:67], v[68:69], s[74:75] op_sel_hi:[1,0]
	v_pk_fma_f32 v[64:65], v[70:71], v[64:65], s[36:37] op_sel_hi:[1,1,0]
	v_exp_f32_e32 v66, v66
	v_exp_f32_e32 v67, v67
	v_pk_fma_f32 v[64:65], v[70:71], v[64:65], s[50:51] op_sel_hi:[1,1,0]
	v_cmp_gt_f32_e32 vcc, 0, v62
	v_pk_fma_f32 v[64:65], v[70:71], v[64:65], s[72:73] op_sel_hi:[1,1,0]
	s_nop 0
	v_pk_mul_f32 v[64:65], v[70:71], v[64:65]
	s_nop 0
	v_pk_mul_f32 v[64:65], v[66:67], v[64:65]
	s_nop 0
	v_pk_mul_f32 v[66:67], v[62:63], v[64:65]
	v_pk_fma_f32 v[64:65], v[62:63], v[64:65], v[62:63] neg_lo:[1,0,0] neg_hi:[1,0,0]
	s_nop 0
	v_cndmask_b32_e32 v62, v64, v66, vcc
	v_mul_f32_e32 v66, 0xbfb8aa3b, v57
	v_mul_f32_e32 v64, 0xbfb8aa3b, v56
	v_exp_f32_e32 v66, v66
	v_exp_f32_e32 v64, v64
	v_cmp_gt_f32_e32 vcc, 0, v63
	v_add_f32_e32 v64, 1.0, v64
	s_nop 0
	v_cndmask_b32_e32 v63, v65, v67, vcc
	v_add_f32_e32 v65, 1.0, v66
	v_mul_f32_e32 v66, 0xbfb8aa3b, v58
	v_mul_f32_e32 v67, 0xbfb8aa3b, v59
	v_exp_f32_e32 v66, v66
	v_exp_f32_e32 v67, v67
	v_rcp_f32_e32 v64, v64
	v_rcp_f32_e32 v65, v65
	v_add_f32_e32 v66, 1.0, v66
	v_add_f32_e32 v67, 1.0, v67
	v_rcp_f32_e32 v66, v66
	v_rcp_f32_e32 v67, v67
	v_pk_mul_f32 v[56:57], v[56:57], v[64:65]
	v_and_b32_e32 v65, 0x7fffffff, v53
	v_and_b32_e32 v64, 0x7fffffff, v52
	v_pk_fma_f32 v[64:65], v[64:65], s[28:29], 1.0 op_sel_hi:[1,0,0]
	v_pk_mul_f32 v[58:59], v[58:59], v[66:67]
	v_rcp_f32_e32 v64, v64
	v_rcp_f32_e32 v65, v65
	v_pk_mul_f32 v[58:59], v[62:63], v[58:59]
	v_pk_mul_f32 v[62:63], v[52:53], v[52:53]
	v_pk_mul_f32 v[56:57], v[60:61], v[56:57]
	v_pk_fma_f32 v[60:61], v[64:65], s[30:31], v[150:151] op_sel_hi:[1,0,0]
	v_pk_mul_f32 v[62:63], v[62:63], s[74:75] op_sel_hi:[1,0]
	v_pk_fma_f32 v[60:61], v[64:65], v[60:61], s[36:37] op_sel_hi:[1,1,0]
	v_exp_f32_e32 v62, v62
	v_exp_f32_e32 v63, v63
	v_pk_fma_f32 v[60:61], v[64:65], v[60:61], s[50:51] op_sel_hi:[1,1,0]
	v_and_b32_e32 v67, 0x7fffffff, v55
	v_and_b32_e32 v66, 0x7fffffff, v54
	v_pk_fma_f32 v[60:61], v[64:65], v[60:61], s[72:73] op_sel_hi:[1,1,0]
	v_pk_fma_f32 v[66:67], v[66:67], s[28:29], 1.0 op_sel_hi:[1,0,0]
	v_pk_mul_f32 v[60:61], v[64:65], v[60:61]
	v_rcp_f32_e32 v66, v66
	v_rcp_f32_e32 v67, v67
	v_pk_mul_f32 v[60:61], v[62:63], v[60:61]
	v_cmp_gt_f32_e32 vcc, 0, v52
	v_pk_mul_f32 v[62:63], v[52:53], v[60:61]
	v_pk_fma_f32 v[60:61], v[52:53], v[60:61], v[52:53] neg_lo:[1,0,0] neg_hi:[1,0,0]
	v_pk_mul_f32 v[64:65], v[54:55], v[54:55]
	v_cndmask_b32_e32 v52, v60, v62, vcc
	v_cmp_gt_f32_e32 vcc, 0, v53
	s_nop 1
	v_cndmask_b32_e32 v53, v61, v63, vcc
	v_pk_fma_f32 v[60:61], v[66:67], s[30:31], v[150:151] op_sel_hi:[1,0,0]
	v_pk_mul_f32 v[62:63], v[64:65], s[74:75] op_sel_hi:[1,0]
	v_pk_fma_f32 v[60:61], v[66:67], v[60:61], s[36:37] op_sel_hi:[1,1,0]
	v_exp_f32_e32 v62, v62
	v_exp_f32_e32 v63, v63
	v_pk_fma_f32 v[60:61], v[66:67], v[60:61], s[50:51] op_sel_hi:[1,1,0]
	v_mul_f32_e32 v64, 0xbfb8aa3b, v48
	v_pk_fma_f32 v[60:61], v[66:67], v[60:61], s[72:73] op_sel_hi:[1,1,0]
	v_exp_f32_e32 v64, v64
	v_mul_f32_e32 v65, 0xbfb8aa3b, v49
	v_pk_mul_f32 v[60:61], v[66:67], v[60:61]
	v_exp_f32_e32 v65, v65
	v_pk_mul_f32 v[60:61], v[62:63], v[60:61]
	v_cmp_gt_f32_e32 vcc, 0, v54
	v_pk_mul_f32 v[62:63], v[54:55], v[60:61]
	v_pk_fma_f32 v[60:61], v[54:55], v[60:61], v[54:55] neg_lo:[1,0,0] neg_hi:[1,0,0]
	s_nop 0
	v_cndmask_b32_e32 v54, v60, v62, vcc
	v_add_f32_e32 v60, 1.0, v64
	v_mul_f32_e32 v62, 0xbfb8aa3b, v50
	v_rcp_f32_e32 v64, v60
	v_add_f32_e32 v60, 1.0, v65
	v_exp_f32_e32 v62, v62
	v_mul_f32_e32 v65, 0xbfb8aa3b, v51
	v_exp_f32_e32 v67, v65
	v_rcp_f32_e32 v65, v60
	v_add_f32_e32 v60, 1.0, v62
	v_rcp_f32_e32 v66, v60
	v_add_f32_e32 v60, 1.0, v67
	v_rcp_f32_e32 v67, v60
	v_cmp_gt_f32_e32 vcc, 0, v55
	v_pk_mul_f32 v[48:49], v[48:49], v[64:65]
	v_pk_mul_f32 v[50:51], v[50:51], v[66:67]
	v_cndmask_b32_e32 v55, v61, v63, vcc
	v_pk_mul_f32 v[54:55], v[54:55], v[50:51]
	v_pk_mul_f32 v[50:51], v[52:53], v[48:49]
	v_and_b32_e32 v53, 0x7fffffff, v45
	v_and_b32_e32 v52, 0x7fffffff, v44
	v_pk_fma_f32 v[52:53], v[52:53], s[28:29], 1.0 op_sel_hi:[1,0,0]
	v_cvt_pk_bf16_f32 v48, v56, v57
	v_cvt_pk_bf16_f32 v49, v58, v59
	v_cvt_pk_bf16_f32 v50, v50, v51
	v_cvt_pk_bf16_f32 v51, v54, v55
	v_add_co_u32_e32 v54, vcc, s6, v148
; __device__ __forceinline__ unsigned cvt_pk_bf16(float lo, float hi) { unsigned r; asm volatile("v_cvt_pk_bf16_f32 %0, %1, %2" : "=v"(r) : "v"(lo), "v"(hi)); return r; }
; __device__ __forceinline__ f32x4 gelu4(f32x4 v) { f32x2 a = gelu_pk((f32x2){v[0], v[1]}), b = gelu_pk((f32x2){v[2], v[3]}); return (f32x4){a.x, a.y, b.x, b.y}; }
; __device__ __forceinline__ f32x4 silu4(f32x4 v) { return v * sigm4(v); }
;     __device__ __forceinline__ void operator()(const f32x4 (&acc)[2][2][4][2], const pg8::Unit& u, int wr, int wc, int fr, int fq) const {
;     ...
;                 for (int m = 0; m < 4; ++m) {
;                     bf16_t* rowp = base + (size_t)(row0 + ai * 128 + m * 16) * 1024;
;                     const f32x4 v0 = gelu4(acc[ai][0][m][0]) * silu4(acc[ai][1][m][0]), v1 = gelu4(acc[ai][0][m][1]) * silu4(acc[ai][1][m][1]);
;                     u32x4 w; w.x = cvt_pk_bf16(v0[0], v0[1]); w.y = cvt_pk_bf16(v0[2], v0[3]); w.z = cvt_pk_bf16(v1[0], v1[1]); w.w = cvt_pk_bf16(v1[2], v1[3]);
;                     __builtin_nontemporal_store(w, (u32x4*)rowp);
	v_rcp_f32_e32 v52, v52
	v_rcp_f32_e32 v53, v53
	v_addc_co_u32_e32 v55, vcc, 0, v149, vcc
	global_store_dwordx4 v[54:55], v[48:51], off nt
	v_and_b32_e32 v55, 0x7fffffff, v47
	v_and_b32_e32 v54, 0x7fffffff, v46
	v_pk_mul_f32 v[50:51], v[44:45], v[44:45]
	v_pk_fma_f32 v[48:49], v[52:53], s[30:31], v[150:151] op_sel_hi:[1,0,0]
	v_pk_mul_f32 v[50:51], v[50:51], s[74:75] op_sel_hi:[1,0]
	v_pk_fma_f32 v[48:49], v[52:53], v[48:49], s[36:37] op_sel_hi:[1,1,0]
	v_exp_f32_e32 v50, v50
	v_exp_f32_e32 v51, v51
	v_pk_fma_f32 v[48:49], v[52:53], v[48:49], s[50:51] op_sel_hi:[1,1,0]
	v_pk_fma_f32 v[54:55], v[54:55], s[28:29], 1.0 op_sel_hi:[1,0,0]
	v_pk_fma_f32 v[48:49], v[52:53], v[48:49], s[72:73] op_sel_hi:[1,1,0]
	v_rcp_f32_e32 v54, v54
	v_pk_mul_f32 v[48:49], v[52:53], v[48:49]
	v_rcp_f32_e32 v55, v55
	v_pk_mul_f32 v[48:49], v[50:51], v[48:49]
	v_cmp_gt_f32_e32 vcc, 0, v44
	v_pk_mul_f32 v[50:51], v[44:45], v[48:49]
	v_pk_fma_f32 v[48:49], v[44:45], v[48:49], v[44:45] neg_lo:[1,0,0] neg_hi:[1,0,0]
	v_pk_mul_f32 v[52:53], v[46:47], v[46:47]
	v_cndmask_b32_e32 v44, v48, v50, vcc
	v_cmp_gt_f32_e32 vcc, 0, v45
	s_mov_b32 s6, 0x48000
	s_nop 0
	v_cndmask_b32_e32 v45, v49, v51, vcc
	v_pk_fma_f32 v[48:49], v[54:55], s[30:31], v[150:151] op_sel_hi:[1,0,0]
	v_pk_mul_f32 v[50:51], v[52:53], s[74:75] op_sel_hi:[1,0]
	v_pk_fma_f32 v[48:49], v[54:55], v[48:49], s[36:37] op_sel_hi:[1,1,0]
	v_exp_f32_e32 v50, v50
	v_exp_f32_e32 v51, v51
	v_pk_fma_f32 v[48:49], v[54:55], v[48:49], s[50:51] op_sel_hi:[1,1,0]
	v_cmp_gt_f32_e32 vcc, 0, v46
	v_pk_fma_f32 v[48:49], v[54:55], v[48:49], s[72:73] op_sel_hi:[1,1,0]
	s_nop 0
	v_pk_mul_f32 v[48:49], v[54:55], v[48:49]
	s_nop 0
	v_pk_mul_f32 v[48:49], v[50:51], v[48:49]
	s_nop 0
	v_pk_mul_f32 v[50:51], v[46:47], v[48:49]
	v_pk_fma_f32 v[48:49], v[46:47], v[48:49], v[46:47] neg_lo:[1,0,0] neg_hi:[1,0,0]
	s_nop 0
	v_cndmask_b32_e32 v46, v48, v50, vcc
	v_mul_f32_e32 v50, 0xbfb8aa3b, v41
	v_mul_f32_e32 v48, 0xbfb8aa3b, v40
	v_exp_f32_e32 v50, v50
	v_exp_f32_e32 v48, v48
	v_cmp_gt_f32_e32 vcc, 0, v47
	v_add_f32_e32 v48, 1.0, v48
	s_nop 0
	v_cndmask_b32_e32 v47, v49, v51, vcc
	v_add_f32_e32 v49, 1.0, v50
	v_mul_f32_e32 v50, 0xbfb8aa3b, v42
	v_mul_f32_e32 v51, 0xbfb8aa3b, v43
	v_exp_f32_e32 v50, v50
	v_exp_f32_e32 v51, v51
	v_rcp_f32_e32 v48, v48
	v_rcp_f32_e32 v49, v49
	v_add_f32_e32 v50, 1.0, v50
	v_add_f32_e32 v51, 1.0, v51
	v_rcp_f32_e32 v50, v50
	v_rcp_f32_e32 v51, v51
	v_pk_mul_f32 v[40:41], v[40:41], v[48:49]
	v_and_b32_e32 v49, 0x7fffffff, v37
	v_and_b32_e32 v48, 0x7fffffff, v36
	v_pk_fma_f32 v[48:49], v[48:49], s[28:29], 1.0 op_sel_hi:[1,0,0]
	v_pk_mul_f32 v[42:43], v[42:43], v[50:51]
	v_rcp_f32_e32 v48, v48
	v_rcp_f32_e32 v49, v49
	v_pk_mul_f32 v[42:43], v[46:47], v[42:43]
	v_pk_mul_f32 v[46:47], v[36:37], v[36:37]
	v_pk_mul_f32 v[40:41], v[44:45], v[40:41]
	v_pk_fma_f32 v[44:45], v[48:49], s[30:31], v[150:151] op_sel_hi:[1,0,0]
	v_pk_mul_f32 v[46:47], v[46:47], s[74:75] op_sel_hi:[1,0]
	v_pk_fma_f32 v[44:45], v[48:49], v[44:45], s[36:37] op_sel_hi:[1,1,0]
	v_exp_f32_e32 v46, v46
	v_exp_f32_e32 v47, v47
	v_pk_fma_f32 v[44:45], v[48:49], v[44:45], s[50:51] op_sel_hi:[1,1,0]
	v_and_b32_e32 v51, 0x7fffffff, v39
	v_and_b32_e32 v50, 0x7fffffff, v38
	v_pk_fma_f32 v[44:45], v[48:49], v[44:45], s[72:73] op_sel_hi:[1,1,0]
	v_pk_fma_f32 v[50:51], v[50:51], s[28:29], 1.0 op_sel_hi:[1,0,0]
	v_pk_mul_f32 v[44:45], v[48:49], v[44:45]
	v_rcp_f32_e32 v50, v50
	v_rcp_f32_e32 v51, v51
	v_pk_mul_f32 v[44:45], v[46:47], v[44:45]
	v_cmp_gt_f32_e32 vcc, 0, v36
	v_pk_mul_f32 v[46:47], v[36:37], v[44:45]
	v_pk_fma_f32 v[44:45], v[36:37], v[44:45], v[36:37] neg_lo:[1,0,0] neg_hi:[1,0,0]
	v_pk_mul_f32 v[48:49], v[38:39], v[38:39]
	v_cndmask_b32_e32 v36, v44, v46, vcc
	v_cmp_gt_f32_e32 vcc, 0, v37
	s_nop 1
	v_cndmask_b32_e32 v37, v45, v47, vcc
	v_pk_fma_f32 v[44:45], v[50:51], s[30:31], v[150:151] op_sel_hi:[1,0,0]
	v_pk_mul_f32 v[46:47], v[48:49], s[74:75] op_sel_hi:[1,0]
	v_pk_fma_f32 v[44:45], v[50:51], v[44:45], s[36:37] op_sel_hi:[1,1,0]
	v_exp_f32_e32 v46, v46
	v_exp_f32_e32 v47, v47
	v_pk_fma_f32 v[44:45], v[50:51], v[44:45], s[50:51] op_sel_hi:[1,1,0]
	v_mul_f32_e32 v48, 0xbfb8aa3b, v32
	v_pk_fma_f32 v[44:45], v[50:51], v[44:45], s[72:73] op_sel_hi:[1,1,0]
	v_exp_f32_e32 v48, v48
	v_mul_f32_e32 v49, 0xbfb8aa3b, v33
	v_pk_mul_f32 v[44:45], v[50:51], v[44:45]
	v_exp_f32_e32 v49, v49
	v_pk_mul_f32 v[44:45], v[46:47], v[44:45]
	v_cmp_gt_f32_e32 vcc, 0, v38
	v_pk_mul_f32 v[46:47], v[38:39], v[44:45]
	v_pk_fma_f32 v[44:45], v[38:39], v[44:45], v[38:39] neg_lo:[1,0,0] neg_hi:[1,0,0]
	s_nop 0
	v_cndmask_b32_e32 v38, v44, v46, vcc
	v_add_f32_e32 v44, 1.0, v48
	v_mul_f32_e32 v46, 0xbfb8aa3b, v34
	v_rcp_f32_e32 v48, v44
	v_add_f32_e32 v44, 1.0, v49
	v_exp_f32_e32 v46, v46
	v_mul_f32_e32 v49, 0xbfb8aa3b, v35
	v_exp_f32_e32 v51, v49
	v_rcp_f32_e32 v49, v44
	v_add_f32_e32 v44, 1.0, v46
	v_rcp_f32_e32 v50, v44
	v_add_f32_e32 v44, 1.0, v51
	v_rcp_f32_e32 v51, v44
	v_cmp_gt_f32_e32 vcc, 0, v39
	v_pk_mul_f32 v[32:33], v[32:33], v[48:49]
	v_pk_mul_f32 v[34:35], v[34:35], v[50:51]
	v_cndmask_b32_e32 v39, v45, v47, vcc
	v_pk_mul_f32 v[38:39], v[38:39], v[34:35]
	v_pk_mul_f32 v[34:35], v[36:37], v[32:33]
	v_and_b32_e32 v37, 0x7fffffff, v29
	v_and_b32_e32 v36, 0x7fffffff, v28
	v_pk_fma_f32 v[36:37], v[36:37], s[28:29], 1.0 op_sel_hi:[1,0,0]
	v_cvt_pk_bf16_f32 v32, v40, v41
	v_cvt_pk_bf16_f32 v33, v42, v43
	v_cvt_pk_bf16_f32 v34, v34, v35
	v_cvt_pk_bf16_f32 v35, v38, v39
	v_add_co_u32_e32 v38, vcc, s6, v148
	v_rcp_f32_e32 v36, v36
	v_rcp_f32_e32 v37, v37
	v_addc_co_u32_e32 v39, vcc, 0, v149, vcc
	global_store_dwordx4 v[38:39], v[32:35], off nt
; __device__ __forceinline__ unsigned cvt_pk_bf16(float lo, float hi) { unsigned r; asm volatile("v_cvt_pk_bf16_f32 %0, %1, %2" : "=v"(r) : "v"(lo), "v"(hi)); return r; }
; __device__ __forceinline__ f32x4 gelu4(f32x4 v) { f32x2 a = gelu_pk((f32x2){v[0], v[1]}), b = gelu_pk((f32x2){v[2], v[3]}); return (f32x4){a.x, a.y, b.x, b.y}; }
; __device__ __forceinline__ f32x4 silu4(f32x4 v) { return v * sigm4(v); }
;     __device__ __forceinline__ void operator()(const f32x4 (&acc)[2][2][4][2], const pg8::Unit& u, int wr, int wc, int fr, int fq) const {
;     ...
;                 for (int m = 0; m < 4; ++m) {
;                     bf16_t* rowp = base + (size_t)(row0 + ai * 128 + m * 16) * 1024;
;                     const f32x4 v0 = gelu4(acc[ai][0][m][0]) * silu4(acc[ai][1][m][0]), v1 = gelu4(acc[ai][0][m][1]) * silu4(acc[ai][1][m][1]);
;                     u32x4 w; w.x = cvt_pk_bf16(v0[0], v0[1]); w.y = cvt_pk_bf16(v0[2], v0[3]); w.z = cvt_pk_bf16(v1[0], v1[1]); w.w = cvt_pk_bf16(v1[2], v1[3]);
;                     __builtin_nontemporal_store(w, (u32x4*)rowp);
	v_and_b32_e32 v39, 0x7fffffff, v31
	v_and_b32_e32 v38, 0x7fffffff, v30
	v_pk_mul_f32 v[34:35], v[28:29], v[28:29]
	v_pk_fma_f32 v[32:33], v[36:37], s[30:31], v[150:151] op_sel_hi:[1,0,0]
	v_pk_mul_f32 v[34:35], v[34:35], s[74:75] op_sel_hi:[1,0]
	v_pk_fma_f32 v[32:33], v[36:37], v[32:33], s[36:37] op_sel_hi:[1,1,0]
	v_exp_f32_e32 v34, v34
	v_exp_f32_e32 v35, v35
	v_pk_fma_f32 v[32:33], v[36:37], v[32:33], s[50:51] op_sel_hi:[1,1,0]
	v_pk_fma_f32 v[38:39], v[38:39], s[28:29], 1.0 op_sel_hi:[1,0,0]
	v_pk_fma_f32 v[32:33], v[36:37], v[32:33], s[72:73] op_sel_hi:[1,1,0]
	v_rcp_f32_e32 v38, v38
	v_pk_mul_f32 v[32:33], v[36:37], v[32:33]
	v_rcp_f32_e32 v39, v39
	v_pk_mul_f32 v[32:33], v[34:35], v[32:33]
	v_cmp_gt_f32_e32 vcc, 0, v28
	v_pk_mul_f32 v[34:35], v[28:29], v[32:33]
	v_pk_fma_f32 v[32:33], v[28:29], v[32:33], v[28:29] neg_lo:[1,0,0] neg_hi:[1,0,0]
	v_pk_mul_f32 v[36:37], v[30:31], v[30:31]
	v_cndmask_b32_e32 v28, v32, v34, vcc
	v_cmp_gt_f32_e32 vcc, 0, v29
	s_mov_b32 s6, 0x50000
	s_nop 0
	v_cndmask_b32_e32 v29, v33, v35, vcc
	v_pk_fma_f32 v[32:33], v[38:39], s[30:31], v[150:151] op_sel_hi:[1,0,0]
	v_pk_mul_f32 v[34:35], v[36:37], s[74:75] op_sel_hi:[1,0]
	v_pk_fma_f32 v[32:33], v[38:39], v[32:33], s[36:37] op_sel_hi:[1,1,0]
	v_exp_f32_e32 v34, v34
	v_exp_f32_e32 v35, v35
	v_pk_fma_f32 v[32:33], v[38:39], v[32:33], s[50:51] op_sel_hi:[1,1,0]
	v_cmp_gt_f32_e32 vcc, 0, v30
	v_pk_fma_f32 v[32:33], v[38:39], v[32:33], s[72:73] op_sel_hi:[1,1,0]
	s_nop 0
	v_pk_mul_f32 v[32:33], v[38:39], v[32:33]
	s_nop 0
	v_pk_mul_f32 v[32:33], v[34:35], v[32:33]
	s_nop 0
	v_pk_mul_f32 v[34:35], v[30:31], v[32:33]
	v_pk_fma_f32 v[32:33], v[30:31], v[32:33], v[30:31] neg_lo:[1,0,0] neg_hi:[1,0,0]
	s_nop 0
	v_cndmask_b32_e32 v30, v32, v34, vcc
	v_mul_f32_e32 v34, 0xbfb8aa3b, v25
	v_mul_f32_e32 v32, 0xbfb8aa3b, v24
	v_exp_f32_e32 v34, v34
	v_exp_f32_e32 v32, v32
	v_cmp_gt_f32_e32 vcc, 0, v31
	v_add_f32_e32 v32, 1.0, v32
	s_nop 0
	v_cndmask_b32_e32 v31, v33, v35, vcc
	v_add_f32_e32 v33, 1.0, v34
	v_mul_f32_e32 v34, 0xbfb8aa3b, v26
	v_mul_f32_e32 v35, 0xbfb8aa3b, v27
	v_exp_f32_e32 v34, v34
	v_exp_f32_e32 v35, v35
	v_rcp_f32_e32 v32, v32
	v_rcp_f32_e32 v33, v33
	v_add_f32_e32 v34, 1.0, v34
	v_add_f32_e32 v35, 1.0, v35
	v_rcp_f32_e32 v34, v34
	v_rcp_f32_e32 v35, v35
	v_pk_mul_f32 v[24:25], v[24:25], v[32:33]
	v_and_b32_e32 v33, 0x7fffffff, v21
	v_and_b32_e32 v32, 0x7fffffff, v20
	v_pk_fma_f32 v[32:33], v[32:33], s[28:29], 1.0 op_sel_hi:[1,0,0]
	v_pk_mul_f32 v[26:27], v[26:27], v[34:35]
	v_rcp_f32_e32 v32, v32
	v_rcp_f32_e32 v33, v33
	v_pk_mul_f32 v[26:27], v[30:31], v[26:27]
	v_pk_mul_f32 v[30:31], v[20:21], v[20:21]
	v_pk_mul_f32 v[24:25], v[28:29], v[24:25]
	v_pk_fma_f32 v[28:29], v[32:33], s[30:31], v[150:151] op_sel_hi:[1,0,0]
	v_pk_mul_f32 v[30:31], v[30:31], s[74:75] op_sel_hi:[1,0]
	v_pk_fma_f32 v[28:29], v[32:33], v[28:29], s[36:37] op_sel_hi:[1,1,0]
	v_exp_f32_e32 v30, v30
	v_exp_f32_e32 v31, v31
	v_pk_fma_f32 v[28:29], v[32:33], v[28:29], s[50:51] op_sel_hi:[1,1,0]
	v_and_b32_e32 v35, 0x7fffffff, v23
	v_and_b32_e32 v34, 0x7fffffff, v22
	v_pk_fma_f32 v[28:29], v[32:33], v[28:29], s[72:73] op_sel_hi:[1,1,0]
	v_pk_fma_f32 v[34:35], v[34:35], s[28:29], 1.0 op_sel_hi:[1,0,0]
	v_pk_mul_f32 v[28:29], v[32:33], v[28:29]
	v_rcp_f32_e32 v34, v34
	v_rcp_f32_e32 v35, v35
	v_pk_mul_f32 v[28:29], v[30:31], v[28:29]
	v_cmp_gt_f32_e32 vcc, 0, v20
	v_pk_mul_f32 v[30:31], v[20:21], v[28:29]
	v_pk_fma_f32 v[28:29], v[20:21], v[28:29], v[20:21] neg_lo:[1,0,0] neg_hi:[1,0,0]
	v_pk_mul_f32 v[32:33], v[22:23], v[22:23]
	v_cndmask_b32_e32 v20, v28, v30, vcc
	v_cmp_gt_f32_e32 vcc, 0, v21
	s_nop 1
	v_cndmask_b32_e32 v21, v29, v31, vcc
	v_pk_fma_f32 v[28:29], v[34:35], s[30:31], v[150:151] op_sel_hi:[1,0,0]
	v_pk_mul_f32 v[30:31], v[32:33], s[74:75] op_sel_hi:[1,0]
	v_pk_fma_f32 v[28:29], v[34:35], v[28:29], s[36:37] op_sel_hi:[1,1,0]
	v_exp_f32_e32 v30, v30
	v_exp_f32_e32 v31, v31
	v_pk_fma_f32 v[28:29], v[34:35], v[28:29], s[50:51] op_sel_hi:[1,1,0]
	v_mul_f32_e32 v32, 0xbfb8aa3b, v16
	v_pk_fma_f32 v[28:29], v[34:35], v[28:29], s[72:73] op_sel_hi:[1,1,0]
	v_exp_f32_e32 v32, v32
	v_mul_f32_e32 v33, 0xbfb8aa3b, v17
	v_pk_mul_f32 v[28:29], v[34:35], v[28:29]
	v_exp_f32_e32 v33, v33
	v_pk_mul_f32 v[28:29], v[30:31], v[28:29]
	v_cmp_gt_f32_e32 vcc, 0, v22
	v_pk_mul_f32 v[30:31], v[22:23], v[28:29]
	v_pk_fma_f32 v[28:29], v[22:23], v[28:29], v[22:23] neg_lo:[1,0,0] neg_hi:[1,0,0]
	s_nop 0
	v_cndmask_b32_e32 v22, v28, v30, vcc
	v_add_f32_e32 v28, 1.0, v32
	v_mul_f32_e32 v30, 0xbfb8aa3b, v18
	v_rcp_f32_e32 v32, v28
	v_add_f32_e32 v28, 1.0, v33
	v_exp_f32_e32 v30, v30
	v_mul_f32_e32 v33, 0xbfb8aa3b, v19
	v_exp_f32_e32 v35, v33
	v_rcp_f32_e32 v33, v28
	v_add_f32_e32 v28, 1.0, v30
	v_rcp_f32_e32 v34, v28
	v_add_f32_e32 v28, 1.0, v35
	v_rcp_f32_e32 v35, v28
	v_cmp_gt_f32_e32 vcc, 0, v23
	v_pk_mul_f32 v[16:17], v[16:17], v[32:33]
	v_pk_mul_f32 v[18:19], v[18:19], v[34:35]
	v_cndmask_b32_e32 v23, v29, v31, vcc
	v_pk_mul_f32 v[22:23], v[22:23], v[18:19]
	v_pk_mul_f32 v[18:19], v[20:21], v[16:17]
	v_and_b32_e32 v21, 0x7fffffff, v13
	v_and_b32_e32 v20, 0x7fffffff, v12
	v_pk_fma_f32 v[20:21], v[20:21], s[28:29], 1.0 op_sel_hi:[1,0,0]
	v_cvt_pk_bf16_f32 v16, v24, v25
	v_cvt_pk_bf16_f32 v17, v26, v27
	v_cvt_pk_bf16_f32 v18, v18, v19
	v_cvt_pk_bf16_f32 v19, v22, v23
	v_add_co_u32_e32 v22, vcc, s6, v148
	v_rcp_f32_e32 v20, v20
	v_rcp_f32_e32 v21, v21
; __device__ __forceinline__ unsigned cvt_pk_bf16(float lo, float hi) { unsigned r; asm volatile("v_cvt_pk_bf16_f32 %0, %1, %2" : "=v"(r) : "v"(lo), "v"(hi)); return r; }
; __device__ __forceinline__ f32x4 gelu4(f32x4 v) { f32x2 a = gelu_pk((f32x2){v[0], v[1]}), b = gelu_pk((f32x2){v[2], v[3]}); return (f32x4){a.x, a.y, b.x, b.y}; }
; __device__ __forceinline__ f32x4 silu4(f32x4 v) { return v * sigm4(v); }
;     __device__ __forceinline__ void operator()(const f32x4 (&acc)[2][2][4][2], const pg8::Unit& u, int wr, int wc, int fr, int fq) const {
;     ...
;                 for (int m = 0; m < 4; ++m) {
;                     bf16_t* rowp = base + (size_t)(row0 + ai * 128 + m * 16) * 1024;
;                     const f32x4 v0 = gelu4(acc[ai][0][m][0]) * silu4(acc[ai][1][m][0]), v1 = gelu4(acc[ai][0][m][1]) * silu4(acc[ai][1][m][1]);
;                     u32x4 w; w.x = cvt_pk_bf16(v0[0], v0[1]); w.y = cvt_pk_bf16(v0[2], v0[3]); w.z = cvt_pk_bf16(v1[0], v1[1]); w.w = cvt_pk_bf16(v1[2], v1[3]);
;                     __builtin_nontemporal_store(w, (u32x4*)rowp);
	v_addc_co_u32_e32 v23, vcc, 0, v149, vcc
	global_store_dwordx4 v[22:23], v[16:19], off nt
	v_and_b32_e32 v23, 0x7fffffff, v15
	v_and_b32_e32 v22, 0x7fffffff, v14
	v_pk_mul_f32 v[18:19], v[12:13], v[12:13]
	v_pk_fma_f32 v[16:17], v[20:21], s[30:31], v[150:151] op_sel_hi:[1,0,0]
	v_pk_mul_f32 v[18:19], v[18:19], s[74:75] op_sel_hi:[1,0]
	v_pk_fma_f32 v[16:17], v[20:21], v[16:17], s[36:37] op_sel_hi:[1,1,0]
	v_exp_f32_e32 v18, v18
	v_exp_f32_e32 v19, v19
	v_pk_fma_f32 v[16:17], v[20:21], v[16:17], s[50:51] op_sel_hi:[1,1,0]
	v_pk_fma_f32 v[22:23], v[22:23], s[28:29], 1.0 op_sel_hi:[1,0,0]
	v_pk_fma_f32 v[16:17], v[20:21], v[16:17], s[72:73] op_sel_hi:[1,1,0]
	v_rcp_f32_e32 v22, v22
	v_pk_mul_f32 v[16:17], v[20:21], v[16:17]
	v_rcp_f32_e32 v23, v23
	v_pk_mul_f32 v[16:17], v[18:19], v[16:17]
	v_cmp_gt_f32_e32 vcc, 0, v12
	v_pk_mul_f32 v[18:19], v[12:13], v[16:17]
	v_pk_fma_f32 v[16:17], v[12:13], v[16:17], v[12:13] neg_lo:[1,0,0] neg_hi:[1,0,0]
	v_pk_mul_f32 v[20:21], v[14:15], v[14:15]
	v_cndmask_b32_e32 v12, v16, v18, vcc
	v_cmp_gt_f32_e32 vcc, 0, v13
	s_nop 1
	v_cndmask_b32_e32 v13, v17, v19, vcc
	v_pk_fma_f32 v[16:17], v[22:23], s[30:31], v[150:151] op_sel_hi:[1,0,0]
	v_pk_mul_f32 v[18:19], v[20:21], s[74:75] op_sel_hi:[1,0]
	v_pk_fma_f32 v[16:17], v[22:23], v[16:17], s[36:37] op_sel_hi:[1,1,0]
	v_exp_f32_e32 v18, v18
	v_exp_f32_e32 v19, v19
	v_pk_fma_f32 v[16:17], v[22:23], v[16:17], s[50:51] op_sel_hi:[1,1,0]
	v_cmp_gt_f32_e32 vcc, 0, v14
	v_pk_fma_f32 v[16:17], v[22:23], v[16:17], s[72:73] op_sel_hi:[1,1,0]
	s_nop 0
	v_pk_mul_f32 v[16:17], v[22:23], v[16:17]
	s_nop 0
	v_pk_mul_f32 v[16:17], v[18:19], v[16:17]
	s_nop 0
	v_pk_mul_f32 v[18:19], v[14:15], v[16:17]
	v_pk_fma_f32 v[16:17], v[14:15], v[16:17], v[14:15] neg_lo:[1,0,0] neg_hi:[1,0,0]
	s_nop 0
	v_cndmask_b32_e32 v14, v16, v18, vcc
	v_mul_f32_e32 v18, 0xbfb8aa3b, v9
	v_mul_f32_e32 v16, 0xbfb8aa3b, v8
	v_exp_f32_e32 v18, v18
	v_exp_f32_e32 v16, v16
	v_cmp_gt_f32_e32 vcc, 0, v15
	v_add_f32_e32 v16, 1.0, v16
	s_nop 0
	v_cndmask_b32_e32 v15, v17, v19, vcc
	v_add_f32_e32 v17, 1.0, v18
	v_mul_f32_e32 v18, 0xbfb8aa3b, v10
	v_mul_f32_e32 v19, 0xbfb8aa3b, v11
	v_exp_f32_e32 v18, v18
	v_exp_f32_e32 v19, v19
	v_rcp_f32_e32 v16, v16
	v_rcp_f32_e32 v17, v17
	v_add_f32_e32 v18, 1.0, v18
	v_add_f32_e32 v19, 1.0, v19
	v_rcp_f32_e32 v18, v18
	v_rcp_f32_e32 v19, v19
	v_pk_mul_f32 v[8:9], v[8:9], v[16:17]
	v_and_b32_e32 v17, 0x7fffffff, v5
	v_and_b32_e32 v16, 0x7fffffff, v4
	v_pk_fma_f32 v[16:17], v[16:17], s[28:29], 1.0 op_sel_hi:[1,0,0]
	v_pk_mul_f32 v[10:11], v[10:11], v[18:19]
	v_rcp_f32_e32 v16, v16
	v_rcp_f32_e32 v17, v17
	v_pk_mul_f32 v[10:11], v[14:15], v[10:11]
	v_pk_mul_f32 v[14:15], v[4:5], v[4:5]
	v_pk_mul_f32 v[8:9], v[12:13], v[8:9]
	v_pk_fma_f32 v[12:13], v[16:17], s[30:31], v[150:151] op_sel_hi:[1,0,0]
	v_pk_mul_f32 v[14:15], v[14:15], s[74:75] op_sel_hi:[1,0]
	v_pk_fma_f32 v[12:13], v[16:17], v[12:13], s[36:37] op_sel_hi:[1,1,0]
	v_exp_f32_e32 v14, v14
	v_exp_f32_e32 v15, v15
	v_pk_fma_f32 v[12:13], v[16:17], v[12:13], s[50:51] op_sel_hi:[1,1,0]
	v_and_b32_e32 v19, 0x7fffffff, v7
	v_and_b32_e32 v18, 0x7fffffff, v6
	v_pk_fma_f32 v[12:13], v[16:17], v[12:13], s[72:73] op_sel_hi:[1,1,0]
	v_pk_fma_f32 v[18:19], v[18:19], s[28:29], 1.0 op_sel_hi:[1,0,0]
	v_pk_mul_f32 v[12:13], v[16:17], v[12:13]
	v_rcp_f32_e32 v18, v18
	v_rcp_f32_e32 v19, v19
	v_pk_mul_f32 v[12:13], v[14:15], v[12:13]
	v_cmp_gt_f32_e32 vcc, 0, v4
	v_pk_mul_f32 v[14:15], v[4:5], v[12:13]
	v_pk_fma_f32 v[12:13], v[4:5], v[12:13], v[4:5] neg_lo:[1,0,0] neg_hi:[1,0,0]
	v_pk_mul_f32 v[16:17], v[6:7], v[6:7]
	v_cndmask_b32_e32 v4, v12, v14, vcc
	v_cmp_gt_f32_e32 vcc, 0, v5
	s_nop 1
	v_cndmask_b32_e32 v5, v13, v15, vcc
	v_pk_fma_f32 v[12:13], v[18:19], s[30:31], v[150:151] op_sel_hi:[1,0,0]
	v_pk_mul_f32 v[14:15], v[16:17], s[74:75] op_sel_hi:[1,0]
	v_pk_fma_f32 v[12:13], v[18:19], v[12:13], s[36:37] op_sel_hi:[1,1,0]
	v_exp_f32_e32 v14, v14
	v_exp_f32_e32 v15, v15
	v_pk_fma_f32 v[12:13], v[18:19], v[12:13], s[50:51] op_sel_hi:[1,1,0]
	v_mul_f32_e32 v16, 0xbfb8aa3b, v0
	v_pk_fma_f32 v[12:13], v[18:19], v[12:13], s[72:73] op_sel_hi:[1,1,0]
	v_exp_f32_e32 v16, v16
	v_mul_f32_e32 v17, 0xbfb8aa3b, v1
	v_pk_mul_f32 v[12:13], v[18:19], v[12:13]
	v_exp_f32_e32 v17, v17
	v_pk_mul_f32 v[12:13], v[14:15], v[12:13]
	v_cmp_gt_f32_e32 vcc, 0, v6
	v_pk_mul_f32 v[14:15], v[6:7], v[12:13]
	v_pk_fma_f32 v[12:13], v[6:7], v[12:13], v[6:7] neg_lo:[1,0,0] neg_hi:[1,0,0]
	s_nop 0
	v_cndmask_b32_e32 v6, v12, v14, vcc
	v_add_f32_e32 v12, 1.0, v16
	v_mul_f32_e32 v14, 0xbfb8aa3b, v2
	v_rcp_f32_e32 v16, v12
	v_add_f32_e32 v12, 1.0, v17
	v_exp_f32_e32 v14, v14
	v_mul_f32_e32 v17, 0xbfb8aa3b, v3
	v_exp_f32_e32 v19, v17
	v_rcp_f32_e32 v17, v12
	v_add_f32_e32 v12, 1.0, v14
	v_rcp_f32_e32 v18, v12
	v_add_f32_e32 v12, 1.0, v19
	v_rcp_f32_e32 v19, v12
	v_cmp_gt_f32_e32 vcc, 0, v7
	v_pk_mul_f32 v[0:1], v[0:1], v[16:17]
	v_pk_mul_f32 v[2:3], v[2:3], v[18:19]
	v_cndmask_b32_e32 v7, v13, v15, vcc
	v_pk_mul_f32 v[6:7], v[6:7], v[2:3]
	v_pk_mul_f32 v[2:3], v[4:5], v[0:1]
	v_add_co_u32_e32 v4, vcc, 0x58000, v148
	v_cvt_pk_bf16_f32 v0, v8, v9
	v_cvt_pk_bf16_f32 v1, v10, v11
	v_cvt_pk_bf16_f32 v2, v2, v3
	v_cvt_pk_bf16_f32 v3, v6, v7
	s_nop 1
	v_addc_co_u32_e32 v5, vcc, 0, v149, vcc
	s_waitcnt vmcnt(7)
	global_store_dwordx4 v[4:5], v[0:3], off nt
	s_andn2_b64 vcc, exec, s[4:5]
	s_mov_b64 s[4:5], -1
	s_cbranch_vccnz .LBB0_152
